# v138 + masked attention path carry products without packed ops/copies
# baseline (speedup 1.0000x reference)
; #define LAS __attribute__((address_space(3)))
; __device__ __forceinline__ void attn_unit(LAS unsigned char* lds, const bf16_t* Qm, const bf16_t* Km, const bf16_t* VT, const bf16_t* GBm, bf16_t* YB, int b, int hp, int qb) {
;     ...
;         if (k0 < qw + 15 && !__all(Rs == 0.f)) {
;             f32x4 s[4];
; #pragma unroll
;             for (int rb = 0; rb < 4; ++rb) {
;                 const int c = rb >> 1, e = rb & 1;
;                 const int kl = 32 * c + (fr >> 2) * 8 + e * 4 + (fr & 3);
;                 s[rb] = (f32x4){0.f, 0.f, 0.f, 0.f};
; #pragma unroll
;                 for (int ks = 0; ks < 4; ++ks) {
;                     const bf16x8 a = *(const LAS bf16x8*)(KL + kl * 272 + (ks * 32 + fq * 8) * 2);
;                     s[rb] = __builtin_amdgcn_mfma_f32_16x16x32_bf16(a, qf[ks], s[rb], 0, 0, 0);
;                 }
;             }
;             const int qi = qw + fr;
;             float be[2][8], om[2][8];
; #pragma unroll
;             for (int c = 0; c < 2; ++c)
; #pragma unroll
;                 for (int i = 0; i < 8; ++i) {
;                     const float z = s[2 * c + (i >> 2)][i & 3];
;                     const int key = k0 + 32 * c + 8 * fq + i;
;                     const float e = __builtin_amdgcn_exp2f(-fabsf(z));
;                     const float r = __builtin_amdgcn_rcpf(1.0f + e);
;                     const bool pos = z >= 0.f, valid = key < qi;
;                     be[c][i] = valid ? (pos ? r : e * r) : 0.f;
;                     om[c][i] = valid ? (pos ? e * r : r) : 1.f;
;                 }
;             float suf[2][8], Gs[2], Tt[2];
; #pragma unroll
;             for (int c = 0; c < 2; ++c) {
;                 float run = 1.f;
; #pragma unroll
;                 for (int i = 7; i >= 0; --i) { suf[c][i] = run; run *= om[c][i]; }
;                 const float t1 = __shfl(run, (lane + 16) & 63), t2 = __shfl(run, (lane + 32) & 63), t3 = __shfl(run, (lane + 48) & 63);
;                 Gs[c] = (fq < 3 ? t1 : 1.f) * (fq < 2 ? t2 : 1.f) * (fq < 1 ? t3 : 1.f);
;                 Tt[c] = (run * t1) * (t2 * t3);
;             }
.LBB0_519:
	s_add_i32 s12, s56, 64
	v_cmp_lt_u32_e32 vcc, s12, v109
	s_and_saveexec_b64 s[58:59], vcc
	s_cbranch_execz .LBB0_522
	v_cmp_eq_f32_e32 vcc, 0, v96
	s_cmp_eq_u64 vcc, exec
	s_cbranch_scc1 .LBB0_522
	v_readfirstlane_b32 s66, v109
	s_add_i32 s67, s12, 64
	s_nop 1
	s_sub_i32 s66, s66, 15
	s_cmp_le_u32 s67, s66
	s_cbranch_scc1 .Lattn_nomask
	ds_read_b128 v[120:123], v116
	ds_read_b128 v[124:127], v116 offset:64
	ds_read_b128 v[128:131], v116 offset:1088
	ds_read_b128 v[132:135], v116 offset:1152
	v_add_u32_e32 v99, s56, v108
	v_add_u32_e32 v103, 64, v99
	s_waitcnt lgkmcnt(3)
	v_mfma_f32_16x16x32_bf16 v[120:123], v[120:123], v[0:3], 0
	s_waitcnt lgkmcnt(2)
	v_mfma_f32_16x16x32_bf16 v[120:123], v[124:127], v[4:7], v[120:123]
	ds_read_b128 v[124:127], v116 offset:128
	ds_read_b128 v[136:139], v116 offset:192
	s_waitcnt lgkmcnt(3)
	v_mfma_f32_16x16x32_bf16 v[128:131], v[128:131], v[0:3], 0
	s_waitcnt lgkmcnt(1)
	v_mfma_f32_16x16x32_bf16 v[120:123], v[124:127], v[8:11], v[120:123]
	ds_read_b128 v[124:127], v116 offset:1216
	ds_read_b128 v[140:143], v116 offset:1280
	ds_read_b128 v[144:147], v116 offset:8704
	ds_read_b128 v[148:151], v116 offset:8768
	v_mfma_f32_16x16x32_bf16 v[128:131], v[132:135], v[4:7], v[128:131]
	ds_read_b128 v[132:135], v116 offset:8832
	ds_read_b128 v[152:155], v116 offset:8896
	ds_read_b128 v[156:159], v116 offset:9792
	ds_read_b128 v[160:163], v116 offset:9856
	s_waitcnt lgkmcnt(8)
	v_mfma_f32_16x16x32_bf16 v[120:123], v[136:139], v[12:15], v[120:123]
	ds_read_b128 v[136:139], v116 offset:9920
	ds_read_b128 v[164:167], v116 offset:9984
	s_waitcnt lgkmcnt(9)
	v_mfma_f32_16x16x32_bf16 v[124:127], v[124:127], v[8:11], v[128:131]
	s_nop 3
	v_exp_f32_e32 v97, v120
	s_nop 0
	v_add_f32_e32 v101, 1.0, v97
	s_waitcnt lgkmcnt(7)
	v_mfma_f32_16x16x32_bf16 v[128:131], v[144:147], v[0:3], 0
	v_rcp_f32_e32 v101, v101
	s_nop 0
	v_mul_f32_e32 v120, v97, v101
	s_waitcnt lgkmcnt(6)
	v_mfma_f32_16x16x32_bf16 v[128:131], v[148:151], v[4:7], v[128:131]
	v_mov_b32_e32 v97, v101
	v_cmp_lt_u32_e32 vcc, v103, v111
	v_mfma_f32_16x16x32_bf16 v[124:127], v[140:143], v[12:15], v[124:127]
	v_exp_f32_e32 v140, v121
	v_exp_f32_e32 v141, v122
	v_cndmask_b32_e32 v101, 0, v120, vcc
	s_waitcnt lgkmcnt(5)
	v_mfma_f32_16x16x32_bf16 v[128:131], v[132:135], v[8:11], v[128:131]
	v_add_f32_e32 v103, 1.0, v140
	v_rcp_f32_e32 v103, v103
	v_add_u32_e32 v120, 0x41, v99
	s_waitcnt lgkmcnt(3)
	v_mfma_f32_16x16x32_bf16 v[132:135], v[156:159], v[0:3], 0
	v_cmp_lt_u32_e64 s[12:13], v120, v111
	v_add_f32_e32 v120, 1.0, v141
	v_rcp_f32_e32 v120, v120
	s_waitcnt lgkmcnt(2)
	v_mfma_f32_16x16x32_bf16 v[132:135], v[160:163], v[4:7], v[132:135]
	v_cndmask_b32_e32 v97, 1.0, v97, vcc
	v_mul_f32_e32 v140, v140, v103
	s_waitcnt lgkmcnt(1)
	v_mfma_f32_16x16x32_bf16 v[132:135], v[136:139], v[8:11], v[132:135]
	v_exp_f32_e32 v136, v123
	v_exp_f32_e32 v137, v124
	v_cndmask_b32_e64 v142, 0, v140, s[12:13]
	v_add_u32_e32 v121, 0x42, v99
	v_mul_f32_e32 v140, v141, v120
	v_cndmask_b32_e64 v103, 1.0, v103, s[12:13]
	v_cmp_lt_u32_e64 s[12:13], v121, v111
	v_add_f32_e32 v121, 1.0, v136
	s_nop 0
	v_cndmask_b32_e64 v143, 0, v140, s[12:13]
	v_add_u32_e32 v122, 0x43, v99
	v_rcp_f32_e32 v121, v121
	v_cndmask_b32_e64 v120, 1.0, v120, s[12:13]
	v_cmp_lt_u32_e64 s[12:13], v122, v111
	v_add_f32_e32 v122, 1.0, v137
	v_rcp_f32_e32 v122, v122
	v_mul_f32_e32 v123, v136, v121
	v_mfma_f32_16x16x32_bf16 v[128:131], v[152:155], v[12:15], v[128:131]
	s_nop 0
	v_mul_f32_e32 v124, v137, v122
	v_exp_f32_e32 v137, v125
	v_cndmask_b32_e64 v144, 0, v123, s[12:13]
	v_add_u32_e32 v123, 0x44, v99
	v_cndmask_b32_e64 v121, 1.0, v121, s[12:13]
	v_cmp_lt_u32_e64 s[12:13], v123, v111
	v_add_f32_e32 v123, 1.0, v137
	v_rcp_f32_e32 v123, v123
	v_exp_f32_e32 v138, v128
	v_exp_f32_e32 v139, v131
	v_mul_f32_e32 v125, v137, v123
	v_exp_f32_e32 v137, v126
	v_cndmask_b32_e64 v145, 0, v124, s[12:13]
	v_add_u32_e32 v124, 0x45, v99
	v_cndmask_b32_e64 v122, 1.0, v122, s[12:13]
	v_cmp_lt_u32_e64 s[12:13], v124, v111
	v_add_f32_e32 v124, 1.0, v137
	v_rcp_f32_e32 v124, v124
	s_waitcnt lgkmcnt(0)
	v_mfma_f32_16x16x32_bf16 v[132:135], v[164:167], v[12:15], v[132:135]
	v_mul_f32_e32 v126, v137, v124
	v_exp_f32_e32 v137, v127
	v_cndmask_b32_e64 v146, 0, v125, s[12:13]
	v_add_u32_e32 v125, 0x46, v99
	v_cndmask_b32_e64 v123, 1.0, v123, s[12:13]
	v_cmp_lt_u32_e64 s[12:13], v125, v111
	v_add_f32_e32 v125, 1.0, v137
	v_add_u32_e32 v136, 0x47, v99
	v_cndmask_b32_e64 v126, 0, v126, s[12:13]
	v_rcp_f32_e32 v125, v125
	v_cndmask_b32_e64 v124, 1.0, v124, s[12:13]
	v_cmp_lt_u32_e64 s[12:13], v136, v111
	v_add_f32_e32 v136, 1.0, v138
	v_rcp_f32_e32 v136, v136
	v_mul_f32_e32 v127, v137, v125
	s_nop 1
	v_mul_f32_e32 v128, v138, v136
	v_exp_f32_e32 v138, v129
	v_cndmask_b32_e64 v147, 1.0, v125, s[12:13]
	v_add_u32_e32 v125, 0x60, v99
	v_cndmask_b32_e64 v127, 0, v127, s[12:13]
	v_cmp_lt_u32_e64 s[12:13], v125, v111
	v_add_f32_e32 v125, 1.0, v138
	v_rcp_f32_e32 v125, v125
	v_mul_f32_e32 v153, v147, v124
	v_mul_f32_e32 v154, v123, v153
	v_mul_f32_e32 v129, v138, v125
	v_exp_f32_e32 v138, v130
	v_cndmask_b32_e64 v140, 1.0, v136, s[12:13]
	v_add_u32_e32 v136, 0x61, v99
	v_cndmask_b32_e64 v128, 0, v128, s[12:13]
	v_cmp_lt_u32_e64 s[12:13], v136, v111
	v_add_f32_e32 v136, 1.0, v138
	v_add_u32_e32 v137, 0x62, v99
	v_cndmask_b32_e64 v129, 0, v129, s[12:13]
	v_rcp_f32_e32 v136, v136
	v_cndmask_b32_e64 v125, 1.0, v125, s[12:13]
	v_cmp_lt_u32_e64 s[12:13], v137, v111
	v_add_f32_e32 v137, 1.0, v139
	v_rcp_f32_e32 v137, v137
	v_mul_f32_e32 v130, v138, v136
	v_mul_f32_e32 v155, v122, v154
	v_mul_f32_e32 v156, v121, v155
	v_mul_f32_e32 v131, v139, v137
; #define LAS __attribute__((address_space(3)))
; __device__ __forceinline__ void attn_unit(LAS unsigned char* lds, const bf16_t* Qm, const bf16_t* Km, const bf16_t* VT, const bf16_t* GBm, bf16_t* YB, int b, int hp, int qb) {
;     ...
;             const int qi = qw + fr;
;             float be[2][8], om[2][8];
; #pragma unroll
;             for (int c = 0; c < 2; ++c)
; #pragma unroll
;                 for (int i = 0; i < 8; ++i) {
;                     const float z = s[2 * c + (i >> 2)][i & 3];
;                     const int key = k0 + 32 * c + 8 * fq + i;
;                     const float e = __builtin_amdgcn_exp2f(-fabsf(z));
;                     const float r = __builtin_amdgcn_rcpf(1.0f + e);
;                     const bool pos = z >= 0.f, valid = key < qi;
;                     be[c][i] = valid ? (pos ? r : e * r) : 0.f;
;                     om[c][i] = valid ? (pos ? e * r : r) : 1.f;
;                 }
;             float suf[2][8], Gs[2], Tt[2];
; #pragma unroll
;             for (int c = 0; c < 2; ++c) {
;                 float run = 1.f;
; #pragma unroll
;                 for (int i = 7; i >= 0; --i) { suf[c][i] = run; run *= om[c][i]; }
;                 const float t1 = __shfl(run, (lane + 16) & 63), t2 = __shfl(run, (lane + 32) & 63), t3 = __shfl(run, (lane + 48) & 63);
;                 Gs[c] = (fq < 3 ? t1 : 1.f) * (fq < 2 ? t2 : 1.f) * (fq < 1 ? t3 : 1.f);
;                 Tt[c] = (run * t1) * (t2 * t3);
;             }
;             bf16x8 pf[2];
; #pragma unroll
;             for (int c = 0; c < 2; ++c) {
;                 const float basec = Rs * Gs[c] * (c == 0 ? Tt[1] : 1.f);
;                 float w[8];
; #pragma unroll
;                 for (int i = 0; i < 8; ++i) w[i] = be[c][i] * (suf[c][i] * basec);
;                 u32x4 pw; pw.x = cvt_pk_bf16(w[0], w[1]); pw.y = cvt_pk_bf16(w[2], w[3]); pw.z = cvt_pk_bf16(w[4], w[5]); pw.w = cvt_pk_bf16(w[6], w[7]);
;                 pf[c] = __builtin_bit_cast(bf16x8, pw);
;             }
;             Rs *= Tt[0] * Tt[1];
; #pragma unroll
;             for (int db = 0; db < 8; ++db)
; #pragma unroll
;                 for (int c = 0; c < 2; ++c) {
;                     const bf16x8 a = *(const LAS bf16x8*)(VL + (db * 16 + fr) * 144 + (32 * c + 8 * fq) * 2);
;                     o[db] = __builtin_amdgcn_mfma_f32_16x16x32_bf16(a, pf[c], o[db], 0, 0, 0);
;                 }
	v_exp_f32_e32 v139, v132
	v_cndmask_b32_e64 v141, 1.0, v136, s[12:13]
	v_add_u32_e32 v136, 0x63, v99
	v_cndmask_b32_e64 v130, 0, v130, s[12:13]
	v_cmp_lt_u32_e64 s[12:13], v136, v111
	v_add_f32_e32 v136, 1.0, v139
	v_rcp_f32_e32 v136, v136
	v_mul_f32_e32 v157, v120, v156
	v_mul_f32_e32 v103, v103, v157
	v_mul_f32_e32 v132, v139, v136
	v_exp_f32_e32 v139, v133
	v_cndmask_b32_e64 v148, 1.0, v137, s[12:13]
	v_add_u32_e32 v137, 0x64, v99
	v_cndmask_b32_e64 v131, 0, v131, s[12:13]
	v_cmp_lt_u32_e64 s[12:13], v137, v111
	v_add_f32_e32 v137, 1.0, v139
	v_rcp_f32_e32 v137, v137
	s_nop 1
	v_mul_f32_e32 v133, v139, v137
	v_exp_f32_e32 v139, v134
	v_cndmask_b32_e64 v149, 1.0, v136, s[12:13]
	v_add_u32_e32 v136, 0x65, v99
	v_cndmask_b32_e64 v132, 0, v132, s[12:13]
	v_cmp_lt_u32_e64 s[12:13], v136, v111
	v_add_f32_e32 v136, 1.0, v139
	v_rcp_f32_e32 v136, v136
	s_nop 1
	v_mul_f32_e32 v138, v139, v136
	v_exp_f32_e32 v139, v135
	v_cndmask_b32_e64 v150, 1.0, v137, s[12:13]
	v_add_u32_e32 v137, 0x66, v99
	v_cndmask_b32_e64 v133, 0, v133, s[12:13]
	v_cmp_lt_u32_e64 s[12:13], v137, v111
	v_add_f32_e32 v137, 1.0, v139
	v_rcp_f32_e32 v151, v137
	v_add_u32_e32 v99, 0x67, v99
	v_mul_f32_e32 v139, v139, v151
	v_cndmask_b32_e64 v134, 0, v138, s[12:13]
	v_cndmask_b32_e64 v152, 1.0, v136, s[12:13]
	v_cmp_lt_u32_e64 s[12:13], v99, v111
	v_mul_f32_e32 v136, v97, v103
	s_nop 0
	v_cndmask_b32_e64 v99, 0, v139, s[12:13]
	v_or_b32_e32 v135, v105, v107
	v_lshlrev_b32_e32 v135, 2, v135
	v_cndmask_b32_e64 v151, 1.0, v151, s[12:13]
	v_xor_b32_e32 v135, 0x80, v135
	v_mul_f32_e32 v152, v151, v152
	ds_bpermute_b32 v137, v135, v136
	ds_bpermute_b32 v138, v118, v136
	v_mul_f32_e32 v150, v150, v152
	v_mul_f32_e32 v149, v149, v150
	v_mul_f32_e32 v148, v148, v149
	v_mul_f32_e32 v158, v141, v148
	v_mul_f32_e32 v159, v125, v158
	ds_bpermute_b32 v139, v119, v136
	s_waitcnt lgkmcnt(2)
	v_cndmask_b32_e64 v97, 1.0, v137, s[10:11]
	s_waitcnt lgkmcnt(1)
	v_cndmask_b32_e64 v120, v138, 1.0, s[0:1]
	v_mul_f32_e32 v121, v140, v159
	v_mul_f32_e32 v97, v120, v97
	ds_bpermute_b32 v120, v135, v121
	ds_bpermute_b32 v123, v118, v121
	ds_bpermute_b32 v122, v119, v121
	s_waitcnt lgkmcnt(3)
	v_cndmask_b32_e64 v124, 1.0, v139, s[4:5]
	v_mul_f32_e32 v124, v97, v124
	s_waitcnt lgkmcnt(2)
	v_cndmask_b32_e64 v97, 1.0, v120, s[10:11]
	s_waitcnt lgkmcnt(1)
	v_cndmask_b32_e64 v125, v123, 1.0, s[0:1]
	v_mul_f32_e32 v97, v125, v97
	s_waitcnt lgkmcnt(0)
	v_cndmask_b32_e64 v125, 1.0, v122, s[4:5]
	v_mul_f32_e32 v120, v120, v122
	v_mul_f32_e32 v121, v121, v123
	v_mul_f32_e32 v135, v97, v125
	v_mul_f32_e32 v140, v96, v124
	v_mul_f32_e32 v141, v120, v121
	v_mul_f32_e32 v97, v140, v141
	v_mul_f32_e32 v120, v156, v97
	v_mul_f32_e32 v121, v143, v120
	v_mul_f32_e32 v120, v155, v97
	v_mul_f32_e32 v122, v144, v120
	v_mul_f32_e32 v120, v154, v97
	v_mul_f32_e32 v103, v103, v97
	v_mul_f32_e32 v123, v145, v120
	v_mul_f32_e32 v120, v153, v97
	v_mul_f32_e32 v101, v101, v103
	v_mul_f32_e32 v103, v157, v97
	v_mul_f32_e32 v124, v146, v120
	v_mul_f32_e32 v120, v147, v97
	v_mul_f32_e32 v97, v127, v97
	v_mul_f32_e32 v103, v142, v103
	v_mul_f32_e32 v125, v126, v120
	v_cvt_pk_bf16_f32 v120, v101, v103
	v_cvt_pk_bf16_f32 v121, v121, v122
	v_cvt_pk_bf16_f32 v122, v123, v124
	v_cvt_pk_bf16_f32 v123, v125, v97
	v_mul_f32_e32 v97, v96, v135
	v_mul_f32_e32 v124, v97, v148
	v_mul_f32_e32 v125, v130, v124
	v_mul_f32_e32 v124, v97, v149
	v_mul_f32_e32 v126, v131, v124
	v_mul_f32_e32 v124, v97, v150
	v_mul_f32_e32 v101, v97, v159
	v_mul_f32_e32 v127, v132, v124
	v_mul_f32_e32 v124, v97, v152
	v_mul_f32_e32 v101, v128, v101
	v_mul_f32_e32 v103, v97, v158
	v_mul_f32_e32 v128, v133, v124
	v_mul_f32_e32 v124, v151, v97
	v_mul_f32_e32 v103, v129, v103
	v_mul_f32_e32 v129, v134, v124
	v_mul_f32_e32 v97, v99, v97
	v_cvt_pk_bf16_f32 v124, v101, v103
	v_cvt_pk_bf16_f32 v125, v125, v126
	v_cvt_pk_bf16_f32 v126, v127, v128
	v_cvt_pk_bf16_f32 v127, v129, v97
	ds_read_b128 v[128:131], v117 offset:17408
	ds_read_b128 v[132:135], v117 offset:17472
	s_waitcnt lgkmcnt(1)
	v_mfma_f32_16x16x32_bf16 v[60:63], v[128:131], v[120:123], v[60:63]
	ds_read_b128 v[128:131], v117 offset:19712
	s_waitcnt lgkmcnt(1)
	v_mfma_f32_16x16x32_bf16 v[60:63], v[132:135], v[124:127], v[60:63]
	ds_read_b128 v[132:135], v117 offset:19776
	s_waitcnt lgkmcnt(1)
	v_mfma_f32_16x16x32_bf16 v[72:75], v[128:131], v[120:123], v[72:75]
	ds_read_b128 v[128:131], v117 offset:22016
	s_waitcnt lgkmcnt(1)
	v_mfma_f32_16x16x32_bf16 v[72:75], v[132:135], v[124:127], v[72:75]
	ds_read_b128 v[132:135], v117 offset:22080
	s_waitcnt lgkmcnt(1)
	v_mfma_f32_16x16x32_bf16 v[56:59], v[128:131], v[120:123], v[56:59]
	ds_read_b128 v[128:131], v117 offset:24320
	s_waitcnt lgkmcnt(1)
	v_mfma_f32_16x16x32_bf16 v[56:59], v[132:135], v[124:127], v[56:59]
	ds_read_b128 v[132:135], v117 offset:24384
	s_waitcnt lgkmcnt(1)
	v_mfma_f32_16x16x32_bf16 v[44:47], v[128:131], v[120:123], v[44:47]
	ds_read_b128 v[128:131], v117 offset:26624
	s_waitcnt lgkmcnt(1)
	v_mfma_f32_16x16x32_bf16 v[44:47], v[132:135], v[124:127], v[44:47]
	ds_read_b128 v[132:135], v117 offset:26688
	s_waitcnt lgkmcnt(1)
	v_mfma_f32_16x16x32_bf16 v[32:35], v[128:131], v[120:123], v[32:35]
	ds_read_b128 v[128:131], v117 offset:28928
	s_waitcnt lgkmcnt(1)
	v_mfma_f32_16x16x32_bf16 v[32:35], v[132:135], v[124:127], v[32:35]
	ds_read_b128 v[132:135], v117 offset:28992
	s_waitcnt lgkmcnt(1)
	v_mfma_f32_16x16x32_bf16 v[24:27], v[128:131], v[120:123], v[24:27]
	ds_read_b128 v[128:131], v117 offset:31232
	s_waitcnt lgkmcnt(1)
	v_mfma_f32_16x16x32_bf16 v[24:27], v[132:135], v[124:127], v[24:27]
	ds_read_b128 v[132:135], v117 offset:31296
	s_waitcnt lgkmcnt(1)
	v_mfma_f32_16x16x32_bf16 v[20:23], v[128:131], v[120:123], v[20:23]
	ds_read_b128 v[128:131], v117 offset:33536
	s_waitcnt lgkmcnt(1)
	v_mfma_f32_16x16x32_bf16 v[20:23], v[132:135], v[124:127], v[20:23]
	ds_read_b128 v[132:135], v117 offset:33600
	s_waitcnt lgkmcnt(1)
	v_mfma_f32_16x16x32_bf16 v[16:19], v[128:131], v[120:123], v[16:19]
	v_mul_f32_e64 v120, v136, v138
	v_mul_f32_e64 v121, v137, v139
	v_mul_f32_e32 v97, v120, v121
	s_waitcnt lgkmcnt(0)
	v_mfma_f32_16x16x32_bf16 v[16:19], v[132:135], v[124:127], v[16:19]
	v_mul_f32_e32 v97, v97, v141
	v_mul_f32_e32 v96, v96, v97
	s_branch .LBB0_522
